# static s_setprio 1 for waves 0-3 (instead of 4-7) inside the MLA and SWA tile loops
# baseline (speedup 1.0000x reference)
.LBB0_561:
	s_waitcnt lgkmcnt(0)
	s_barrier
	s_cmp_lt_u32 s3, 4
	s_cbranch_scc0 .Lmla_prio_done
	s_setprio 1

.LBB0_741:
	s_cmp_lt_u32 s3, 4
	s_cbranch_scc0 .Lswa_prio_done
	s_setprio 1
